# sample-row (64x64 tile) GEMM K-loops of the output and down projections: counted vmcnt(8) at the three LDS staging points, tail chunk loads unconditional (inside d_ws), instead of a full vmcnt(0) drai
# speedup vs baseline: 1.0025x; 1.0025x over previous
.LBB0_1224:
	s_ashr_i32 s10, s12, 31
	s_lshr_b32 s10, s10, 30
	s_add_i32 s10, s12, s10
	s_and_b32 s11, s10, 0x3fffffc
	s_sub_i32 s11, s12, s11
	s_lshl_b32 s13, s11, 6
	v_add_u32_e32 v2, s13, v67
	s_lshl_b32 s14, s10, 4
	v_ashrrev_i32_e32 v3, 31, v2
	s_andn2_b32 s14, s14, 63
	v_lshlrev_b64 v[2:3], 13, v[2:3]
	v_add_u32_e32 v4, s14, v67
	v_lshl_add_u64 v[16:17], v[62:63], 0, v[2:3]
	v_ashrrev_i32_e32 v5, 31, v4
	s_waitcnt vmcnt(0)
	v_lshlrev_b64 v[44:45], 13, v[4:5]
	v_add_co_u32_e32 v14, vcc, s3, v16
	v_lshl_add_u64 v[12:13], v[64:65], 0, v[44:45]
	s_nop 0
	v_addc_co_u32_e32 v15, vcc, 0, v17, vcc
	v_add_co_u32_e32 v8, vcc, s3, v12
	v_lshl_add_u64 v[70:71], s[80:81], 0, v[2:3]
	s_nop 0
	v_addc_co_u32_e32 v9, vcc, 0, v13, vcc
	global_load_dwordx4 v[32:35], v[8:9], off offset:512
	global_load_dwordx4 v[40:43], v[8:9], off offset:256
	global_load_dwordx4 v[28:31], v[12:13], off offset:512
	global_load_dwordx4 v[36:39], v[12:13], off offset:256
	global_load_dwordx4 v[4:7], v[14:15], off offset:512
	global_load_dwordx4 v[52:55], v[8:9], off
	s_nop 0
	global_load_dwordx4 v[8:11], v[16:17], off offset:512
	global_load_dwordx4 v[48:51], v[12:13], off
	global_load_dwordx4 v[20:23], v[14:15], off offset:256
	global_load_dwordx4 v[24:27], v[14:15], off
	s_nop 0
	global_load_dwordx4 v[12:15], v[16:17], off offset:256
	s_nop 0
	global_load_dwordx4 v[16:19], v[16:17], off
	v_mov_b32_e32 v2, v0
	v_mov_b32_e32 v3, v0
	v_lshl_add_u64 v[72:73], s[80:81], 0, v[44:45]
	v_mov_b32_e32 v1, v0
	v_mov_b64_e32 v[58:59], v[2:3]
	v_mov_b64_e32 v[46:47], v[2:3]
	s_mov_b32 s15, -3
	s_mov_b32 s16, 0
	v_mov_b64_e32 v[56:57], v[0:1]
	v_mov_b64_e32 v[44:45], v[0:1]
	s_waitcnt vmcnt(0)
	s_branch .LBB0_1227

.LBB0_1227:
	s_and_b32 s17, s16, 64
	s_mul_i32 s10, s17, 0x110
	s_add_i32 s15, s15, 3
	s_add_i32 s18, s10, 0
	s_cmp_gt_u32 s15, 28
	s_cselect_b64 s[10:11], -1, 0
	v_add3_u32 v3, s18, v74, v60
	s_and_b64 vcc, exec, s[10:11]
	s_waitcnt vmcnt(8)
	ds_write_b128 v3, v[16:19]
	ds_write_b128 v3, v[24:27] offset:8704
	ds_write_b128 v3, v[48:51] offset:34816
	ds_write_b128 v3, v[52:55] offset:43520
	s_waitcnt lgkmcnt(0)
	s_barrier
	v_lshl_add_u64 v[16:17], v[70:71], 0, v[68:69]
	v_add_co_u32_e32 v18, vcc, 0x4f890000, v16
	v_lshl_add_u64 v[48:49], v[72:73], 0, v[68:69]
	s_nop 0
	v_addc_co_u32_e32 v19, vcc, 0, v17, vcc
	v_add_co_u32_e32 v24, vcc, 0x4f8d0000, v16
	s_nop 1
	v_addc_co_u32_e32 v25, vcc, 0, v17, vcc
	v_add_co_u32_e32 v50, vcc, 0xf500000, v48
	global_load_dwordx4 v[16:19], v[18:19], off offset:768
	s_nop 0
	global_load_dwordx4 v[24:27], v[24:25], off offset:768
	v_addc_co_u32_e32 v51, vcc, 0, v49, vcc
	v_add_co_u32_e32 v52, vcc, 0xf540000, v48
	s_nop 1
	v_addc_co_u32_e32 v53, vcc, 0, v49, vcc
	global_load_dwordx4 v[48:51], v[50:51], off offset:768
	s_nop 0
	global_load_dwordx4 v[52:55], v[52:53], off offset:768
.LBB0_1229:
	v_add3_u32 v2, s18, v75, v76
	ds_read_b128 v[80:83], v2 offset:34816
	v_add3_u32 v1, s18, v77, v76
	ds_read_b128 v[84:87], v1
	ds_read_b128 v[88:91], v2 offset:34880
	ds_read_b128 v[92:95], v1 offset:64
	s_xor_b32 s17, s17, 64
	s_mulk_i32 s17, 0x110
	s_add_i32 s17, s17, 0
	v_add3_u32 v79, s17, v74, v60
	s_cmp_gt_u32 s15, 27
	s_waitcnt lgkmcnt(2)
	v_mfma_f32_16x16x32_bf16 v[56:59], v[80:83], v[84:87], v[56:59]
	ds_read_b128 v[84:87], v1 offset:4352
	ds_read_b128 v[96:99], v1 offset:4416
	s_waitcnt lgkmcnt(1)
	v_mfma_f32_16x16x32_bf16 v[44:47], v[80:83], v[84:87], v[44:47]
	v_mfma_f32_16x16x32_bf16 v[56:59], v[88:91], v[92:95], v[56:59]
	ds_read_b128 v[80:83], v2 offset:34944
	ds_read_b128 v[84:87], v1 offset:128
	ds_read_b128 v[92:95], v2 offset:35008
	s_waitcnt lgkmcnt(3)
	v_mfma_f32_16x16x32_bf16 v[44:47], v[88:91], v[96:99], v[44:47]
	ds_read_b128 v[88:91], v1 offset:192
	ds_read_b128 v[96:99], v1 offset:4480
	ds_read_b128 v[100:103], v1 offset:4544
	s_waitcnt vmcnt(8)
	ds_write_b128 v79, v[12:15]
	ds_write_b128 v79, v[20:23] offset:8704
	ds_write_b128 v79, v[36:39] offset:34816
	ds_write_b128 v79, v[40:43] offset:43520
	s_waitcnt lgkmcnt(8)
	v_mfma_f32_16x16x32_bf16 v[56:59], v[80:83], v[84:87], v[56:59]
	s_waitcnt lgkmcnt(0)
	s_barrier
	v_mfma_f32_16x16x32_bf16 v[80:83], v[80:83], v[96:99], v[44:47]
	v_mfma_f32_16x16x32_bf16 v[44:47], v[92:95], v[88:91], v[56:59]
	v_mfma_f32_16x16x32_bf16 v[56:59], v[92:95], v[100:103], v[80:83]
	v_lshl_add_u64 v[12:13], v[70:71], 0, v[68:69]
	v_add_co_u32_e32 v14, vcc, 0x4f890000, v12
	v_lshl_add_u64 v[36:37], v[72:73], 0, v[68:69]
	s_nop 0
	v_addc_co_u32_e32 v15, vcc, 0, v13, vcc
	v_add_co_u32_e32 v20, vcc, 0x4f8d0000, v12
	s_nop 1
	v_addc_co_u32_e32 v21, vcc, 0, v13, vcc
	v_add_co_u32_e32 v38, vcc, 0xf500000, v36
	global_load_dwordx4 v[12:15], v[14:15], off offset:1024
	s_nop 0
	global_load_dwordx4 v[20:23], v[20:21], off offset:1024
	v_addc_co_u32_e32 v39, vcc, 0, v37, vcc
	v_add_co_u32_e32 v40, vcc, 0xf540000, v36
	s_nop 1
	v_addc_co_u32_e32 v41, vcc, 0, v37, vcc
	global_load_dwordx4 v[36:39], v[38:39], off offset:1024
	s_nop 0
	global_load_dwordx4 v[40:43], v[40:41], off offset:1024
.LBB0_1231:
	v_add3_u32 v79, s17, v75, v76
	s_nop 3
	ds_read_b128 v[80:83], v79 offset:34816
	v_add3_u32 v100, s17, v77, v76
	ds_read_b128 v[84:87], v100
	ds_read_b128 v[88:91], v79 offset:34880
	ds_read_b128 v[92:95], v100 offset:64
	s_cmp_gt_u32 s15, 29
	s_waitcnt lgkmcnt(2)
	v_mfma_f32_16x16x32_bf16 v[44:47], v[80:83], v[84:87], v[44:47]
	ds_read_b128 v[84:87], v100 offset:4352
	ds_read_b128 v[96:99], v100 offset:4416
	s_waitcnt lgkmcnt(1)
	v_mfma_f32_16x16x32_bf16 v[56:59], v[80:83], v[84:87], v[56:59]
	ds_read_b128 v[80:83], v79 offset:34944
	v_mfma_f32_16x16x32_bf16 v[44:47], v[88:91], v[92:95], v[44:47]
	s_waitcnt lgkmcnt(1)
	v_mfma_f32_16x16x32_bf16 v[56:59], v[88:91], v[96:99], v[56:59]
	ds_read_b128 v[84:87], v100 offset:128
	ds_read_b128 v[88:91], v79 offset:35008
	ds_read_b128 v[92:95], v100 offset:192
	s_waitcnt lgkmcnt(2)
	v_mfma_f32_16x16x32_bf16 v[44:47], v[80:83], v[84:87], v[44:47]
	ds_read_b128 v[84:87], v100 offset:4480
	ds_read_b128 v[96:99], v100 offset:4544
	s_waitcnt lgkmcnt(1)
	v_mfma_f32_16x16x32_bf16 v[80:83], v[80:83], v[84:87], v[56:59]
	v_mfma_f32_16x16x32_bf16 v[56:59], v[88:91], v[92:95], v[44:47]
	s_waitcnt lgkmcnt(0)
	v_mfma_f32_16x16x32_bf16 v[44:47], v[88:91], v[96:99], v[80:83]
	s_cbranch_scc1 .LBB0_1226
	s_cmp_gt_u32 s15, 26
	s_waitcnt vmcnt(8)
	ds_write_b128 v3, v[8:11]
	ds_write_b128 v3, v[4:7] offset:8704
	ds_write_b128 v3, v[28:31] offset:34816
	ds_write_b128 v3, v[32:35] offset:43520
	s_waitcnt lgkmcnt(0)
	s_barrier
	v_lshl_add_u64 v[4:5], v[70:71], 0, v[68:69]
	v_add_co_u32_e32 v6, vcc, 0x4f890000, v4
	v_lshl_add_u64 v[28:29], v[72:73], 0, v[68:69]
	s_nop 0
	v_addc_co_u32_e32 v7, vcc, 0, v5, vcc
	v_add_co_u32_e32 v4, vcc, 0x4f8d0000, v4
	s_nop 1
	v_addc_co_u32_e32 v5, vcc, 0, v5, vcc
	v_add_co_u32_e32 v30, vcc, 0xf500000, v28
	global_load_dwordx4 v[8:11], v[6:7], off offset:1280
	s_nop 0
	global_load_dwordx4 v[4:7], v[4:5], off offset:1280
	v_addc_co_u32_e32 v31, vcc, 0, v29, vcc
	v_add_co_u32_e32 v32, vcc, 0xf540000, v28
	s_nop 1
	v_addc_co_u32_e32 v33, vcc, 0, v29, vcc
	global_load_dwordx4 v[28:31], v[30:31], off offset:1280
	s_nop 0
	global_load_dwordx4 v[32:35], v[32:33], off offset:1280
	s_branch .LBB0_1225
.LBB0_1234:
	s_waitcnt vmcnt(0)
	v_add_u32_e32 v4, s13, v61
	v_ashrrev_i32_e32 v5, 31, v4
	s_ashr_i32 s10, s14, 31
	v_lshlrev_b64 v[6:7], 13, v[4:5]
	v_mov_b32_e32 v3, s10
	v_or_b32_e32 v2, s14, v66
	v_lshl_add_u64 v[6:7], s[92:93], 0, v[6:7]
	v_lshl_add_u64 v[10:11], v[2:3], 1, v[6:7]
	global_load_dwordx2 v[6:7], v[10:11], off
	v_and_b32_e32 v8, 64, v78
	v_add_u32_e32 v14, 64, v8
	v_xor_b32_e32 v1, 16, v78
	v_cmp_lt_i32_e32 vcc, v1, v14
	s_waitcnt vmcnt(0)
	v_and_b32_e32 v9, 0xffff0000, v6
	v_lshlrev_b32_e32 v8, 16, v6
	v_and_b32_e32 v13, 0xffff0000, v7
	v_lshlrev_b32_e32 v12, 16, v7
	v_pk_add_f32 v[6:7], v[58:59], v[12:13]
	v_pk_add_f32 v[8:9], v[56:57], v[8:9]
	v_cvt_pk_bf16_f32 v13, v6, v7
	v_cndmask_b32_e32 v1, v78, v1, vcc
	v_cvt_pk_bf16_f32 v12, v8, v9
	v_and_b32_e32 v9, 0xffff0000, v13
	v_and_b32_e32 v7, 0xffff0000, v12
	v_lshlrev_b32_e32 v6, 16, v12
	v_lshlrev_b32_e32 v8, 16, v13
	v_mul_f32_e32 v7, v7, v7
	v_mul_f32_e32 v9, v9, v9
	v_fmac_f32_e32 v7, v6, v6
	v_fmac_f32_e32 v9, v8, v8
	v_lshlrev_b32_e32 v1, 2, v1
	v_add_f32_e32 v6, v7, v9
	ds_bpermute_b32 v7, v1, v6
	v_xor_b32_e32 v8, 32, v78
	v_cmp_lt_i32_e32 vcc, v8, v14
	global_store_dwordx2 v[10:11], v[12:13], off
	s_waitcnt lgkmcnt(0)
	v_add_f32_e32 v7, v6, v7
	v_cndmask_b32_e32 v8, v78, v8, vcc
	v_lshlrev_b32_e32 v6, 2, v8
	ds_bpermute_b32 v8, v6, v7
	s_and_saveexec_b64 s[10:11], s[0:1]
	s_cbranch_execz .LBB0_1236
	s_waitcnt lgkmcnt(0)
	v_add_f32_e32 v7, v7, v8
	v_mul_f32_e32 v7, 0x4b800000, v7
	v_trunc_f32_e32 v7, v7
	v_mul_f32_e32 v8, 0x2f800000, v7
	v_floor_f32_e32 v9, v8
	v_fmac_f32_e32 v7, 0xcf800000, v9
	v_cvt_u32_f32_e32 v8, v7
	v_cvt_u32_f32_e32 v9, v9
	v_lshl_add_u64 v[10:11], v[4:5], 3, s[8:9]
	global_atomic_add_x2 v[10:11], v[8:9], off

.LBB0_1541:
	s_ashr_i32 s6, s12, 31
	s_lshr_b32 s6, s6, 30
	s_add_i32 s14, s12, s6
	s_and_b32 s6, s14, 0x3fffffc
	s_sub_i32 s6, s12, s6
	s_lshl_b32 s13, s6, 6
	v_add_u32_e32 v1, s13, v67
	s_lshl_b32 s14, s14, 4
	v_mad_i64_i32 v[2:3], s[6:7], v1, s3, v[62:63]
	s_andn2_b32 s14, s14, 63
	s_waitcnt vmcnt(0)
	v_add_u32_e32 v44, s14, v67
	v_add_co_u32_e32 v14, vcc, 0xac000, v2
	v_mad_i64_i32 v[12:13], s[6:7], v44, s3, v[64:65]
	s_nop 0
	v_addc_co_u32_e32 v15, vcc, 0, v3, vcc
	v_add_co_u32_e32 v8, vcc, 0xac000, v12
	v_mad_i64_i32 v[72:73], s[6:7], v1, s3, v[70:71]
	s_nop 0
	v_addc_co_u32_e32 v9, vcc, 0, v13, vcc
	global_load_dwordx4 v[32:35], v[8:9], off offset:512
	global_load_dwordx4 v[40:43], v[8:9], off offset:256
	global_load_dwordx4 v[28:31], v[12:13], off offset:512
	global_load_dwordx4 v[36:39], v[12:13], off offset:256
	global_load_dwordx4 v[4:7], v[14:15], off offset:512
	global_load_dwordx4 v[52:55], v[8:9], off
	s_nop 0
	global_load_dwordx4 v[8:11], v[2:3], off offset:512
	global_load_dwordx4 v[48:51], v[12:13], off
	global_load_dwordx4 v[20:23], v[14:15], off offset:256
	global_load_dwordx4 v[24:27], v[14:15], off
	s_nop 0
	global_load_dwordx4 v[12:15], v[2:3], off offset:256
	global_load_dwordx4 v[16:19], v[2:3], off
	v_mov_b32_e32 v2, v0
	v_mov_b32_e32 v3, v0
	v_mad_i64_i32 v[74:75], s[6:7], v44, s3, v[70:71]
	v_mov_b32_e32 v1, v0
	v_mov_b64_e32 v[58:59], v[2:3]
	v_mov_b64_e32 v[46:47], v[2:3]
	s_mov_b32 s15, -3
	s_mov_b32 s16, 0
	v_mov_b64_e32 v[56:57], v[0:1]
	v_mov_b64_e32 v[44:45], v[0:1]
	s_waitcnt vmcnt(0)
	s_branch .LBB0_1544

.LBB0_1544:
	s_and_b32 s17, s16, 64
	s_mul_i32 s6, s17, 0x110
	s_add_i32 s15, s15, 3
	s_add_i32 s18, s6, 0
	s_cmpk_gt_u32 s15, 0x52
	s_cselect_b64 s[6:7], -1, 0
	v_add3_u32 v3, s18, v76, v60
	s_and_b64 vcc, exec, s[6:7]
	s_waitcnt vmcnt(8)
	ds_write_b128 v3, v[16:19]
	ds_write_b128 v3, v[24:27] offset:8704
	ds_write_b128 v3, v[48:51] offset:34816
	ds_write_b128 v3, v[52:55] offset:43520
	s_waitcnt lgkmcnt(0)
	s_barrier
	v_lshl_add_u64 v[16:17], v[72:73], 0, v[68:69]
	v_add_co_u32_e32 v18, vcc, 0x81150000, v16
	v_lshl_add_u64 v[48:49], v[74:75], 0, v[68:69]
	s_nop 0
	v_addc_co_u32_e32 v19, vcc, 0, v17, vcc
	v_add_co_u32_e32 v24, vcc, 0x811fc000, v16
	s_nop 1
	v_addc_co_u32_e32 v25, vcc, 0, v17, vcc
	v_add_co_u32_e32 v50, vcc, 0x28d00000, v48
	global_load_dwordx4 v[16:19], v[18:19], off offset:768
	s_nop 0
	global_load_dwordx4 v[24:27], v[24:25], off offset:768
	v_addc_co_u32_e32 v51, vcc, 0, v49, vcc
	v_add_co_u32_e32 v52, vcc, 0x28dac000, v48
	s_nop 1
	v_addc_co_u32_e32 v53, vcc, 0, v49, vcc
	global_load_dwordx4 v[48:51], v[50:51], off offset:768
	s_nop 0
	global_load_dwordx4 v[52:55], v[52:53], off offset:768
.LBB0_1546:
	v_add3_u32 v2, s18, v77, v78
	ds_read_b128 v[82:85], v2 offset:34816
	v_add3_u32 v1, s18, v79, v78
	ds_read_b128 v[86:89], v1
	ds_read_b128 v[90:93], v2 offset:34880
	ds_read_b128 v[94:97], v1 offset:64
	s_xor_b32 s17, s17, 64
	s_mulk_i32 s17, 0x110
	s_add_i32 s17, s17, 0
	v_add3_u32 v81, s17, v76, v60
	s_cmpk_gt_u32 s15, 0x51
	s_waitcnt lgkmcnt(2)
	v_mfma_f32_16x16x32_bf16 v[56:59], v[82:85], v[86:89], v[56:59]
	ds_read_b128 v[86:89], v1 offset:4352
	ds_read_b128 v[98:101], v1 offset:4416
	s_waitcnt lgkmcnt(1)
	v_mfma_f32_16x16x32_bf16 v[44:47], v[82:85], v[86:89], v[44:47]
	v_mfma_f32_16x16x32_bf16 v[56:59], v[90:93], v[94:97], v[56:59]
	ds_read_b128 v[82:85], v2 offset:34944
	ds_read_b128 v[86:89], v1 offset:128
	ds_read_b128 v[94:97], v2 offset:35008
	s_waitcnt lgkmcnt(3)
	v_mfma_f32_16x16x32_bf16 v[44:47], v[90:93], v[98:101], v[44:47]
	ds_read_b128 v[90:93], v1 offset:192
	ds_read_b128 v[98:101], v1 offset:4480
	ds_read_b128 v[102:105], v1 offset:4544
	s_waitcnt vmcnt(8)
	ds_write_b128 v81, v[12:15]
	ds_write_b128 v81, v[20:23] offset:8704
	ds_write_b128 v81, v[36:39] offset:34816
	ds_write_b128 v81, v[40:43] offset:43520
	s_waitcnt lgkmcnt(8)
	v_mfma_f32_16x16x32_bf16 v[56:59], v[82:85], v[86:89], v[56:59]
	s_waitcnt lgkmcnt(0)
	s_barrier
	v_mfma_f32_16x16x32_bf16 v[82:85], v[82:85], v[98:101], v[44:47]
	v_mfma_f32_16x16x32_bf16 v[44:47], v[94:97], v[90:93], v[56:59]
	v_mfma_f32_16x16x32_bf16 v[56:59], v[94:97], v[102:105], v[82:85]
	v_lshl_add_u64 v[12:13], v[72:73], 0, v[68:69]
	v_add_co_u32_e32 v14, vcc, 0x81150000, v12
	v_lshl_add_u64 v[36:37], v[74:75], 0, v[68:69]
	s_nop 0
	v_addc_co_u32_e32 v15, vcc, 0, v13, vcc
	v_add_co_u32_e32 v20, vcc, 0x811fc000, v12
	s_nop 1
	v_addc_co_u32_e32 v21, vcc, 0, v13, vcc
	v_add_co_u32_e32 v38, vcc, 0x28d00000, v36
	global_load_dwordx4 v[12:15], v[14:15], off offset:1024
	s_nop 0
	global_load_dwordx4 v[20:23], v[20:21], off offset:1024
	v_addc_co_u32_e32 v39, vcc, 0, v37, vcc
	v_add_co_u32_e32 v40, vcc, 0x28dac000, v36
	s_nop 1
	v_addc_co_u32_e32 v41, vcc, 0, v37, vcc
	global_load_dwordx4 v[36:39], v[38:39], off offset:1024
	s_nop 0
	global_load_dwordx4 v[40:43], v[40:41], off offset:1024
.LBB0_1548:
	v_add3_u32 v81, s17, v77, v78
	s_nop 3
	ds_read_b128 v[82:85], v81 offset:34816
	v_add3_u32 v102, s17, v79, v78
	ds_read_b128 v[86:89], v102
	ds_read_b128 v[90:93], v81 offset:34880
	ds_read_b128 v[94:97], v102 offset:64
	s_cmpk_gt_u32 s15, 0x53
	s_waitcnt lgkmcnt(2)
	v_mfma_f32_16x16x32_bf16 v[44:47], v[82:85], v[86:89], v[44:47]
	ds_read_b128 v[86:89], v102 offset:4352
	ds_read_b128 v[98:101], v102 offset:4416
	s_waitcnt lgkmcnt(1)
	v_mfma_f32_16x16x32_bf16 v[56:59], v[82:85], v[86:89], v[56:59]
	ds_read_b128 v[82:85], v81 offset:34944
	v_mfma_f32_16x16x32_bf16 v[44:47], v[90:93], v[94:97], v[44:47]
	s_waitcnt lgkmcnt(1)
	v_mfma_f32_16x16x32_bf16 v[56:59], v[90:93], v[98:101], v[56:59]
	ds_read_b128 v[86:89], v102 offset:128
	ds_read_b128 v[90:93], v81 offset:35008
	ds_read_b128 v[94:97], v102 offset:192
	s_waitcnt lgkmcnt(2)
	v_mfma_f32_16x16x32_bf16 v[44:47], v[82:85], v[86:89], v[44:47]
	ds_read_b128 v[86:89], v102 offset:4480
	ds_read_b128 v[98:101], v102 offset:4544
	s_waitcnt lgkmcnt(1)
	v_mfma_f32_16x16x32_bf16 v[82:85], v[82:85], v[86:89], v[56:59]
	v_mfma_f32_16x16x32_bf16 v[56:59], v[90:93], v[94:97], v[44:47]
	s_waitcnt lgkmcnt(0)
	v_mfma_f32_16x16x32_bf16 v[44:47], v[90:93], v[98:101], v[82:85]
	s_cbranch_scc1 .LBB0_1543
	s_cmpk_gt_u32 s15, 0x50
	s_waitcnt vmcnt(8)
	ds_write_b128 v3, v[8:11]
	ds_write_b128 v3, v[4:7] offset:8704
	ds_write_b128 v3, v[28:31] offset:34816
	ds_write_b128 v3, v[32:35] offset:43520
	s_waitcnt lgkmcnt(0)
	s_barrier
	v_lshl_add_u64 v[4:5], v[72:73], 0, v[68:69]
	v_add_co_u32_e32 v6, vcc, 0x81150000, v4
	v_lshl_add_u64 v[28:29], v[74:75], 0, v[68:69]
	s_nop 0
	v_addc_co_u32_e32 v7, vcc, 0, v5, vcc
	v_add_co_u32_e32 v4, vcc, 0x811fc000, v4
	s_nop 1
	v_addc_co_u32_e32 v5, vcc, 0, v5, vcc
	v_add_co_u32_e32 v30, vcc, 0x28d00000, v28
	global_load_dwordx4 v[8:11], v[6:7], off offset:1280
	s_nop 0
	global_load_dwordx4 v[4:7], v[4:5], off offset:1280
	v_addc_co_u32_e32 v31, vcc, 0, v29, vcc
	v_add_co_u32_e32 v32, vcc, 0x28dac000, v28
	s_nop 1
	v_addc_co_u32_e32 v33, vcc, 0, v29, vcc
	global_load_dwordx4 v[28:31], v[30:31], off offset:1280
	s_nop 0
	global_load_dwordx4 v[32:35], v[32:33], off offset:1280
	s_branch .LBB0_1542
.LBB0_1551:
	s_waitcnt vmcnt(0)
	v_add_u32_e32 v4, s13, v61
	v_ashrrev_i32_e32 v5, 31, v4
	s_ashr_i32 s6, s14, 31
	v_lshlrev_b64 v[6:7], 13, v[4:5]
	v_mov_b32_e32 v3, s6
	v_or_b32_e32 v2, s14, v66
	v_lshl_add_u64 v[6:7], s[92:93], 0, v[6:7]
	v_lshl_add_u64 v[10:11], v[2:3], 1, v[6:7]
	global_load_dwordx2 v[6:7], v[10:11], off
	v_and_b32_e32 v8, 64, v80
	v_add_u32_e32 v14, 64, v8
	v_xor_b32_e32 v1, 16, v80
	v_cmp_lt_i32_e32 vcc, v1, v14
	s_waitcnt vmcnt(0)
	v_and_b32_e32 v9, 0xffff0000, v6
	v_lshlrev_b32_e32 v8, 16, v6
	v_and_b32_e32 v13, 0xffff0000, v7
	v_lshlrev_b32_e32 v12, 16, v7
	v_pk_add_f32 v[6:7], v[58:59], v[12:13]
	v_pk_add_f32 v[8:9], v[56:57], v[8:9]
	v_cvt_pk_bf16_f32 v13, v6, v7
	v_cndmask_b32_e32 v1, v80, v1, vcc
	v_cvt_pk_bf16_f32 v12, v8, v9
	v_and_b32_e32 v9, 0xffff0000, v13
	v_and_b32_e32 v7, 0xffff0000, v12
	v_lshlrev_b32_e32 v6, 16, v12
	v_lshlrev_b32_e32 v8, 16, v13
	v_mul_f32_e32 v7, v7, v7
	v_mul_f32_e32 v9, v9, v9
	v_fmac_f32_e32 v7, v6, v6
	v_fmac_f32_e32 v9, v8, v8
	v_lshlrev_b32_e32 v1, 2, v1
	v_add_f32_e32 v6, v7, v9
	ds_bpermute_b32 v7, v1, v6
	v_xor_b32_e32 v8, 32, v80
	v_cmp_lt_i32_e32 vcc, v8, v14
	global_store_dwordx2 v[10:11], v[12:13], off
	s_waitcnt lgkmcnt(0)
	v_add_f32_e32 v7, v6, v7
	v_cndmask_b32_e32 v8, v80, v8, vcc
	v_lshlrev_b32_e32 v6, 2, v8
	ds_bpermute_b32 v8, v6, v7
	s_and_saveexec_b64 s[6:7], s[0:1]
	s_cbranch_execz .LBB0_1553
	s_waitcnt lgkmcnt(0)
	v_add_f32_e32 v7, v7, v8
	v_mul_f32_e32 v7, 0x4b800000, v7
	v_trunc_f32_e32 v7, v7
	v_mul_f32_e32 v8, 0x2f800000, v7
	v_floor_f32_e32 v9, v8
	v_fmac_f32_e32 v7, 0xcf800000, v9
	v_cvt_u32_f32_e32 v8, v7
	v_cvt_u32_f32_e32 v9, v9
	v_lshl_add_u64 v[10:11], v[4:5], 3, s[10:11]
	global_atomic_add_x2 v[10:11], v[8:9], off

.LBB0_2796:
	s_ashr_i32 s10, s12, 31
	s_lshr_b32 s10, s10, 30
	s_add_i32 s10, s12, s10
	s_and_b32 s11, s10, 0x3fffffc
	s_sub_i32 s11, s12, s11
	s_lshl_b32 s13, s11, 6
	v_add_u32_e32 v2, s13, v67
	s_lshl_b32 s14, s10, 4
	v_ashrrev_i32_e32 v3, 31, v2
	s_andn2_b32 s14, s14, 63
	v_lshlrev_b64 v[2:3], 13, v[2:3]
	v_add_u32_e32 v4, s14, v67
	s_waitcnt vmcnt(0)
	v_lshl_add_u64 v[52:53], v[62:63], 0, v[2:3]
	v_ashrrev_i32_e32 v5, 31, v4
	v_lshlrev_b64 v[54:55], 13, v[4:5]
	v_add_co_u32_e32 v58, vcc, s3, v52
	v_lshl_add_u64 v[56:57], v[64:65], 0, v[54:55]
	s_nop 0
	v_addc_co_u32_e32 v59, vcc, 0, v53, vcc
	v_add_co_u32_e32 v70, vcc, s3, v56
	v_lshl_add_u64 v[72:73], s[80:81], 0, v[54:55]
	s_nop 0
	v_addc_co_u32_e32 v71, vcc, 0, v57, vcc
	global_load_dwordx4 v[32:35], v[70:71], off offset:512
	global_load_dwordx4 v[40:43], v[70:71], off offset:256
	global_load_dwordx4 v[28:31], v[56:57], off offset:512
	global_load_dwordx4 v[36:39], v[56:57], off offset:256
	global_load_dwordx4 v[4:7], v[58:59], off offset:512
	global_load_dwordx4 v[48:51], v[70:71], off
	global_load_dwordx4 v[8:11], v[52:53], off offset:512
	global_load_dwordx4 v[44:47], v[56:57], off
	global_load_dwordx4 v[20:23], v[58:59], off offset:256
	global_load_dwordx4 v[24:27], v[58:59], off
	global_load_dwordx4 v[12:15], v[52:53], off offset:256
	global_load_dwordx4 v[16:19], v[52:53], off
	v_lshl_add_u64 v[70:71], s[80:81], 0, v[2:3]
	v_mov_b32_e32 v2, v0
	v_mov_b32_e32 v3, v0
	v_mov_b32_e32 v1, v0
	v_mov_b64_e32 v[58:59], v[2:3]
	v_mov_b64_e32 v[54:55], v[2:3]
	s_mov_b32 s15, -3
	s_mov_b32 s16, 0
	v_mov_b64_e32 v[56:57], v[0:1]
	v_mov_b64_e32 v[52:53], v[0:1]
	s_waitcnt vmcnt(0)
	s_branch .LBB0_2799

.LBB0_2799:
	s_and_b32 s17, s16, 64
	s_mul_i32 s10, s17, 0x110
	s_add_i32 s15, s15, 3
	s_add_i32 s18, s10, 0
	s_cmp_gt_u32 s15, 28
	s_cselect_b64 s[10:11], -1, 0
	v_add3_u32 v3, s18, v74, v60
	s_and_b64 vcc, exec, s[10:11]
	s_waitcnt vmcnt(8)
	ds_write_b128 v3, v[16:19]
	ds_write_b128 v3, v[24:27] offset:8704
	ds_write_b128 v3, v[44:47] offset:34816
	ds_write_b128 v3, v[48:51] offset:43520
	s_waitcnt lgkmcnt(0)
	s_barrier
	v_lshl_add_u64 v[16:17], v[70:71], 0, v[68:69]
	v_add_co_u32_e32 v46, vcc, 0x4f890000, v16
	v_lshl_add_u64 v[44:45], v[72:73], 0, v[68:69]
	s_nop 0
	v_addc_co_u32_e32 v47, vcc, 0, v17, vcc
	v_add_co_u32_e32 v48, vcc, 0x4f8d0000, v16
	s_nop 1
	v_addc_co_u32_e32 v49, vcc, 0, v17, vcc
	v_add_co_u32_e32 v80, vcc, 0x11500000, v44
	global_load_dwordx4 v[16:19], v[46:47], off offset:768
	global_load_dwordx4 v[24:27], v[48:49], off offset:768
	v_addc_co_u32_e32 v81, vcc, 0, v45, vcc
	v_add_co_u32_e32 v82, vcc, 0x11540000, v44
	s_nop 1
	v_addc_co_u32_e32 v83, vcc, 0, v45, vcc
	global_load_dwordx4 v[44:47], v[80:81], off offset:768
	global_load_dwordx4 v[48:51], v[82:83], off offset:768
.LBB0_2801:
	v_add3_u32 v2, s18, v75, v76
	ds_read_b128 v[80:83], v2 offset:34816
	v_add3_u32 v1, s18, v77, v76
	ds_read_b128 v[84:87], v1
	ds_read_b128 v[88:91], v2 offset:34880
	ds_read_b128 v[92:95], v1 offset:64
	s_xor_b32 s17, s17, 64
	s_mulk_i32 s17, 0x110
	s_add_i32 s17, s17, 0
	v_add3_u32 v79, s17, v74, v60
	s_cmp_gt_u32 s15, 27
	s_waitcnt lgkmcnt(2)
	v_mfma_f32_16x16x32_bf16 v[56:59], v[80:83], v[84:87], v[56:59]
	ds_read_b128 v[84:87], v1 offset:4352
	ds_read_b128 v[96:99], v1 offset:4416
	s_waitcnt lgkmcnt(1)
	v_mfma_f32_16x16x32_bf16 v[52:55], v[80:83], v[84:87], v[52:55]
	v_mfma_f32_16x16x32_bf16 v[56:59], v[88:91], v[92:95], v[56:59]
	ds_read_b128 v[80:83], v2 offset:34944
	ds_read_b128 v[84:87], v1 offset:128
	ds_read_b128 v[92:95], v2 offset:35008
	s_waitcnt lgkmcnt(3)
	v_mfma_f32_16x16x32_bf16 v[52:55], v[88:91], v[96:99], v[52:55]
	ds_read_b128 v[88:91], v1 offset:192
	ds_read_b128 v[96:99], v1 offset:4480
	ds_read_b128 v[100:103], v1 offset:4544
	s_waitcnt vmcnt(8)
	ds_write_b128 v79, v[12:15]
	ds_write_b128 v79, v[20:23] offset:8704
	ds_write_b128 v79, v[36:39] offset:34816
	ds_write_b128 v79, v[40:43] offset:43520
	s_waitcnt lgkmcnt(8)
	v_mfma_f32_16x16x32_bf16 v[56:59], v[80:83], v[84:87], v[56:59]
	s_waitcnt lgkmcnt(0)
	s_barrier
	v_mfma_f32_16x16x32_bf16 v[80:83], v[80:83], v[96:99], v[52:55]
	v_mfma_f32_16x16x32_bf16 v[52:55], v[92:95], v[88:91], v[56:59]
	v_mfma_f32_16x16x32_bf16 v[56:59], v[92:95], v[100:103], v[80:83]
	v_lshl_add_u64 v[12:13], v[70:71], 0, v[68:69]
	v_add_co_u32_e32 v38, vcc, 0x4f890000, v12
	v_lshl_add_u64 v[36:37], v[72:73], 0, v[68:69]
	s_nop 0
	v_addc_co_u32_e32 v39, vcc, 0, v13, vcc
	v_add_co_u32_e32 v40, vcc, 0x4f8d0000, v12
	s_nop 1
	v_addc_co_u32_e32 v41, vcc, 0, v13, vcc
	v_add_co_u32_e32 v80, vcc, 0x11500000, v36
	global_load_dwordx4 v[12:15], v[38:39], off offset:1024
	global_load_dwordx4 v[20:23], v[40:41], off offset:1024
	v_addc_co_u32_e32 v81, vcc, 0, v37, vcc
	v_add_co_u32_e32 v82, vcc, 0x11540000, v36
	s_nop 1
	v_addc_co_u32_e32 v83, vcc, 0, v37, vcc
	global_load_dwordx4 v[36:39], v[80:81], off offset:1024
	global_load_dwordx4 v[40:43], v[82:83], off offset:1024
.LBB0_2803:
	v_add3_u32 v79, s17, v75, v76
	s_nop 3
	ds_read_b128 v[80:83], v79 offset:34816
	v_add3_u32 v100, s17, v77, v76
	ds_read_b128 v[84:87], v100
	ds_read_b128 v[88:91], v79 offset:34880
	ds_read_b128 v[92:95], v100 offset:64
	s_cmp_gt_u32 s15, 29
	s_waitcnt lgkmcnt(2)
	v_mfma_f32_16x16x32_bf16 v[52:55], v[80:83], v[84:87], v[52:55]
	ds_read_b128 v[84:87], v100 offset:4352
	ds_read_b128 v[96:99], v100 offset:4416
	s_waitcnt lgkmcnt(1)
	v_mfma_f32_16x16x32_bf16 v[56:59], v[80:83], v[84:87], v[56:59]
	ds_read_b128 v[80:83], v79 offset:34944
	v_mfma_f32_16x16x32_bf16 v[52:55], v[88:91], v[92:95], v[52:55]
	s_waitcnt lgkmcnt(1)
	v_mfma_f32_16x16x32_bf16 v[56:59], v[88:91], v[96:99], v[56:59]
	ds_read_b128 v[84:87], v100 offset:128
	ds_read_b128 v[88:91], v79 offset:35008
	ds_read_b128 v[92:95], v100 offset:192
	s_waitcnt lgkmcnt(2)
	v_mfma_f32_16x16x32_bf16 v[52:55], v[80:83], v[84:87], v[52:55]
	ds_read_b128 v[84:87], v100 offset:4480
	ds_read_b128 v[96:99], v100 offset:4544
	s_waitcnt lgkmcnt(1)
	v_mfma_f32_16x16x32_bf16 v[80:83], v[80:83], v[84:87], v[56:59]
	v_mfma_f32_16x16x32_bf16 v[56:59], v[88:91], v[92:95], v[52:55]
	s_waitcnt lgkmcnt(0)
	v_mfma_f32_16x16x32_bf16 v[52:55], v[88:91], v[96:99], v[80:83]
	s_cbranch_scc1 .LBB0_2798
	s_cmp_gt_u32 s15, 26
	s_waitcnt vmcnt(8)
	ds_write_b128 v3, v[8:11]
	ds_write_b128 v3, v[4:7] offset:8704
	ds_write_b128 v3, v[28:31] offset:34816
	ds_write_b128 v3, v[32:35] offset:43520
	s_waitcnt lgkmcnt(0)
	s_barrier
	v_lshl_add_u64 v[4:5], v[70:71], 0, v[68:69]
	v_add_co_u32_e32 v30, vcc, 0x4f890000, v4
	v_lshl_add_u64 v[28:29], v[72:73], 0, v[68:69]
	s_nop 0
	v_addc_co_u32_e32 v31, vcc, 0, v5, vcc
	v_add_co_u32_e32 v32, vcc, 0x4f8d0000, v4
	s_nop 1
	v_addc_co_u32_e32 v33, vcc, 0, v5, vcc
	v_add_co_u32_e32 v80, vcc, 0x11500000, v28
	global_load_dwordx4 v[8:11], v[30:31], off offset:1280
	global_load_dwordx4 v[4:7], v[32:33], off offset:1280
	v_addc_co_u32_e32 v81, vcc, 0, v29, vcc
	v_add_co_u32_e32 v82, vcc, 0x11540000, v28
	s_nop 1
	v_addc_co_u32_e32 v83, vcc, 0, v29, vcc
	global_load_dwordx4 v[28:31], v[80:81], off offset:1280
	global_load_dwordx4 v[32:35], v[82:83], off offset:1280
	s_branch .LBB0_2797
.LBB0_2806:
	s_waitcnt vmcnt(0)
	v_add_u32_e32 v4, s13, v61
	v_ashrrev_i32_e32 v5, 31, v4
	s_ashr_i32 s10, s14, 31
	v_lshlrev_b64 v[6:7], 13, v[4:5]
	v_mov_b32_e32 v3, s10
	v_or_b32_e32 v2, s14, v66
	v_lshl_add_u64 v[6:7], s[96:97], 0, v[6:7]
	v_lshl_add_u64 v[10:11], v[2:3], 1, v[6:7]
	global_load_dwordx2 v[6:7], v[10:11], off
	v_and_b32_e32 v8, 64, v78
	v_add_u32_e32 v14, 64, v8
	v_xor_b32_e32 v1, 16, v78
	v_cmp_lt_i32_e32 vcc, v1, v14
	s_waitcnt vmcnt(0)
	v_and_b32_e32 v9, 0xffff0000, v6
	v_lshlrev_b32_e32 v8, 16, v6
	v_and_b32_e32 v13, 0xffff0000, v7
	v_lshlrev_b32_e32 v12, 16, v7
	v_pk_add_f32 v[6:7], v[58:59], v[12:13]
	v_pk_add_f32 v[8:9], v[56:57], v[8:9]
	v_cvt_pk_bf16_f32 v13, v6, v7
	v_cndmask_b32_e32 v1, v78, v1, vcc
	v_cvt_pk_bf16_f32 v12, v8, v9
	v_and_b32_e32 v9, 0xffff0000, v13
	v_and_b32_e32 v7, 0xffff0000, v12
	v_lshlrev_b32_e32 v6, 16, v12
	v_lshlrev_b32_e32 v8, 16, v13
	v_mul_f32_e32 v7, v7, v7
	v_mul_f32_e32 v9, v9, v9
	v_fmac_f32_e32 v7, v6, v6
	v_fmac_f32_e32 v9, v8, v8
	v_lshlrev_b32_e32 v1, 2, v1
	v_add_f32_e32 v6, v7, v9
	ds_bpermute_b32 v7, v1, v6
	v_xor_b32_e32 v8, 32, v78
	v_cmp_lt_i32_e32 vcc, v8, v14
	global_store_dwordx2 v[10:11], v[12:13], off
	s_waitcnt lgkmcnt(0)
	v_add_f32_e32 v7, v6, v7
	v_cndmask_b32_e32 v8, v78, v8, vcc
	v_lshlrev_b32_e32 v6, 2, v8
	ds_bpermute_b32 v8, v6, v7
	s_and_saveexec_b64 s[10:11], s[0:1]
	s_cbranch_execz .LBB0_2808
	s_waitcnt lgkmcnt(0)
	v_add_f32_e32 v7, v7, v8
	v_mul_f32_e32 v7, 0x4b800000, v7
	v_trunc_f32_e32 v7, v7
	v_mul_f32_e32 v8, 0x2f800000, v7
	v_floor_f32_e32 v9, v8
	v_fmac_f32_e32 v7, 0xcf800000, v9
	v_cvt_u32_f32_e32 v8, v7
	v_cvt_u32_f32_e32 v9, v9
	v_lshl_add_u64 v[10:11], v[4:5], 3, s[8:9]
	global_atomic_add_x2 v[10:11], v[8:9], off

.LBB0_3113:
	s_ashr_i32 s6, s12, 31
	s_lshr_b32 s6, s6, 30
	s_add_i32 s14, s12, s6
	s_and_b32 s6, s14, 0x3fffffc
	s_sub_i32 s6, s12, s6
	s_lshl_b32 s13, s6, 6
	v_add_u32_e32 v1, s13, v67
	s_lshl_b32 s14, s14, 4
	v_mad_i64_i32 v[2:3], s[6:7], v1, s3, v[62:63]
	s_andn2_b32 s14, s14, 63
	s_waitcnt vmcnt(0)
	v_add_u32_e32 v58, s14, v67
	v_add_co_u32_e32 v54, vcc, 0xac000, v2
	v_mad_i64_i32 v[52:53], s[6:7], v58, s3, v[64:65]
	s_nop 0
	v_addc_co_u32_e32 v55, vcc, 0, v3, vcc
	v_add_co_u32_e32 v56, vcc, 0xac000, v52
	v_mad_i64_i32 v[72:73], s[6:7], v1, s3, v[70:71]
	s_nop 0
	v_addc_co_u32_e32 v57, vcc, 0, v53, vcc
	global_load_dwordx4 v[32:35], v[56:57], off offset:512
	global_load_dwordx4 v[40:43], v[56:57], off offset:256
	global_load_dwordx4 v[28:31], v[52:53], off offset:512
	global_load_dwordx4 v[36:39], v[52:53], off offset:256
	global_load_dwordx4 v[4:7], v[54:55], off offset:512
	global_load_dwordx4 v[48:51], v[56:57], off
	global_load_dwordx4 v[8:11], v[2:3], off offset:512
	global_load_dwordx4 v[44:47], v[52:53], off
	global_load_dwordx4 v[20:23], v[54:55], off offset:256
	global_load_dwordx4 v[24:27], v[54:55], off
	global_load_dwordx4 v[12:15], v[2:3], off offset:256
	global_load_dwordx4 v[16:19], v[2:3], off
	v_mov_b32_e32 v2, v0
	v_mov_b32_e32 v3, v0
	v_mad_i64_i32 v[74:75], s[6:7], v58, s3, v[70:71]
	v_mov_b32_e32 v1, v0
	v_mov_b64_e32 v[58:59], v[2:3]
	v_mov_b64_e32 v[54:55], v[2:3]
	s_mov_b32 s15, -3
	s_mov_b32 s16, 0
	v_mov_b64_e32 v[56:57], v[0:1]
	v_mov_b64_e32 v[52:53], v[0:1]
	s_waitcnt vmcnt(0)
	s_branch .LBB0_3116

.LBB0_3116:
	s_and_b32 s17, s16, 64
	s_mul_i32 s6, s17, 0x110
	s_add_i32 s15, s15, 3
	s_add_i32 s18, s6, 0
	s_cmpk_gt_u32 s15, 0x52
	s_cselect_b64 s[6:7], -1, 0
	v_add3_u32 v3, s18, v76, v60
	s_and_b64 vcc, exec, s[6:7]
	s_waitcnt vmcnt(8)
	ds_write_b128 v3, v[16:19]
	ds_write_b128 v3, v[24:27] offset:8704
	ds_write_b128 v3, v[44:47] offset:34816
	ds_write_b128 v3, v[48:51] offset:43520
	s_waitcnt lgkmcnt(0)
	s_barrier
	v_lshl_add_u64 v[16:17], v[72:73], 0, v[68:69]
	v_add_co_u32_e32 v46, vcc, 0x81150000, v16
	v_lshl_add_u64 v[44:45], v[74:75], 0, v[68:69]
	s_nop 0
	v_addc_co_u32_e32 v47, vcc, 0, v17, vcc
	v_add_co_u32_e32 v48, vcc, 0x811fc000, v16
	s_nop 1
	v_addc_co_u32_e32 v49, vcc, 0, v17, vcc
	v_add_co_u32_e32 v82, vcc, 0x2e300000, v44
	global_load_dwordx4 v[16:19], v[46:47], off offset:768
	global_load_dwordx4 v[24:27], v[48:49], off offset:768
	v_addc_co_u32_e32 v83, vcc, 0, v45, vcc
	v_add_co_u32_e32 v84, vcc, 0x2e3ac000, v44
	s_nop 1
	v_addc_co_u32_e32 v85, vcc, 0, v45, vcc
	global_load_dwordx4 v[44:47], v[82:83], off offset:768
	global_load_dwordx4 v[48:51], v[84:85], off offset:768
.LBB0_3118:
	v_add3_u32 v2, s18, v77, v78
	ds_read_b128 v[82:85], v2 offset:34816
	v_add3_u32 v1, s18, v79, v78
	ds_read_b128 v[86:89], v1
	ds_read_b128 v[90:93], v2 offset:34880
	ds_read_b128 v[94:97], v1 offset:64
	s_xor_b32 s17, s17, 64
	s_mulk_i32 s17, 0x110
	s_add_i32 s17, s17, 0
	v_add3_u32 v81, s17, v76, v60
	s_cmpk_gt_u32 s15, 0x51
	s_waitcnt lgkmcnt(2)
	v_mfma_f32_16x16x32_bf16 v[56:59], v[82:85], v[86:89], v[56:59]
	ds_read_b128 v[86:89], v1 offset:4352
	ds_read_b128 v[98:101], v1 offset:4416
	s_waitcnt lgkmcnt(1)
	v_mfma_f32_16x16x32_bf16 v[52:55], v[82:85], v[86:89], v[52:55]
	v_mfma_f32_16x16x32_bf16 v[56:59], v[90:93], v[94:97], v[56:59]
	ds_read_b128 v[82:85], v2 offset:34944
	ds_read_b128 v[86:89], v1 offset:128
	ds_read_b128 v[94:97], v2 offset:35008
	s_waitcnt lgkmcnt(3)
	v_mfma_f32_16x16x32_bf16 v[52:55], v[90:93], v[98:101], v[52:55]
	ds_read_b128 v[90:93], v1 offset:192
	ds_read_b128 v[98:101], v1 offset:4480
	ds_read_b128 v[102:105], v1 offset:4544
	s_waitcnt vmcnt(8)
	ds_write_b128 v81, v[12:15]
	ds_write_b128 v81, v[20:23] offset:8704
	ds_write_b128 v81, v[36:39] offset:34816
	ds_write_b128 v81, v[40:43] offset:43520
	s_waitcnt lgkmcnt(8)
	v_mfma_f32_16x16x32_bf16 v[56:59], v[82:85], v[86:89], v[56:59]
	s_waitcnt lgkmcnt(0)
	s_barrier
	v_mfma_f32_16x16x32_bf16 v[82:85], v[82:85], v[98:101], v[52:55]
	v_mfma_f32_16x16x32_bf16 v[52:55], v[94:97], v[90:93], v[56:59]
	v_mfma_f32_16x16x32_bf16 v[56:59], v[94:97], v[102:105], v[82:85]
	v_lshl_add_u64 v[12:13], v[72:73], 0, v[68:69]
	v_add_co_u32_e32 v38, vcc, 0x81150000, v12
	v_lshl_add_u64 v[36:37], v[74:75], 0, v[68:69]
	s_nop 0
	v_addc_co_u32_e32 v39, vcc, 0, v13, vcc
	v_add_co_u32_e32 v40, vcc, 0x811fc000, v12
	s_nop 1
	v_addc_co_u32_e32 v41, vcc, 0, v13, vcc
	v_add_co_u32_e32 v82, vcc, 0x2e300000, v36
	global_load_dwordx4 v[12:15], v[38:39], off offset:1024
	global_load_dwordx4 v[20:23], v[40:41], off offset:1024
	v_addc_co_u32_e32 v83, vcc, 0, v37, vcc
	v_add_co_u32_e32 v84, vcc, 0x2e3ac000, v36
	s_nop 1
	v_addc_co_u32_e32 v85, vcc, 0, v37, vcc
	global_load_dwordx4 v[36:39], v[82:83], off offset:1024
	global_load_dwordx4 v[40:43], v[84:85], off offset:1024
.LBB0_3120:
	v_add3_u32 v81, s17, v77, v78
	s_nop 3
	ds_read_b128 v[82:85], v81 offset:34816
	v_add3_u32 v102, s17, v79, v78
	ds_read_b128 v[86:89], v102
	ds_read_b128 v[90:93], v81 offset:34880
	ds_read_b128 v[94:97], v102 offset:64
	s_cmpk_gt_u32 s15, 0x53
	s_waitcnt lgkmcnt(2)
	v_mfma_f32_16x16x32_bf16 v[52:55], v[82:85], v[86:89], v[52:55]
	ds_read_b128 v[86:89], v102 offset:4352
	ds_read_b128 v[98:101], v102 offset:4416
	s_waitcnt lgkmcnt(1)
	v_mfma_f32_16x16x32_bf16 v[56:59], v[82:85], v[86:89], v[56:59]
	ds_read_b128 v[82:85], v81 offset:34944
	v_mfma_f32_16x16x32_bf16 v[52:55], v[90:93], v[94:97], v[52:55]
	s_waitcnt lgkmcnt(1)
	v_mfma_f32_16x16x32_bf16 v[56:59], v[90:93], v[98:101], v[56:59]
	ds_read_b128 v[86:89], v102 offset:128
	ds_read_b128 v[90:93], v81 offset:35008
	ds_read_b128 v[94:97], v102 offset:192
	s_waitcnt lgkmcnt(2)
	v_mfma_f32_16x16x32_bf16 v[52:55], v[82:85], v[86:89], v[52:55]
	ds_read_b128 v[86:89], v102 offset:4480
	ds_read_b128 v[98:101], v102 offset:4544
	s_waitcnt lgkmcnt(1)
	v_mfma_f32_16x16x32_bf16 v[82:85], v[82:85], v[86:89], v[56:59]
	v_mfma_f32_16x16x32_bf16 v[56:59], v[90:93], v[94:97], v[52:55]
	s_waitcnt lgkmcnt(0)
	v_mfma_f32_16x16x32_bf16 v[52:55], v[90:93], v[98:101], v[82:85]
	s_cbranch_scc1 .LBB0_3115
	s_cmpk_gt_u32 s15, 0x50
	s_waitcnt vmcnt(8)
	ds_write_b128 v3, v[8:11]
	ds_write_b128 v3, v[4:7] offset:8704
	ds_write_b128 v3, v[28:31] offset:34816
	ds_write_b128 v3, v[32:35] offset:43520
	s_waitcnt lgkmcnt(0)
	s_barrier
	v_lshl_add_u64 v[4:5], v[72:73], 0, v[68:69]
	v_add_co_u32_e32 v30, vcc, 0x81150000, v4
	v_lshl_add_u64 v[28:29], v[74:75], 0, v[68:69]
	s_nop 0
	v_addc_co_u32_e32 v31, vcc, 0, v5, vcc
	v_add_co_u32_e32 v32, vcc, 0x811fc000, v4
	s_nop 1
	v_addc_co_u32_e32 v33, vcc, 0, v5, vcc
	v_add_co_u32_e32 v82, vcc, 0x2e300000, v28
	global_load_dwordx4 v[8:11], v[30:31], off offset:1280
	global_load_dwordx4 v[4:7], v[32:33], off offset:1280
	v_addc_co_u32_e32 v83, vcc, 0, v29, vcc
	v_add_co_u32_e32 v84, vcc, 0x2e3ac000, v28
	s_nop 1
	v_addc_co_u32_e32 v85, vcc, 0, v29, vcc
	global_load_dwordx4 v[28:31], v[82:83], off offset:1280
	global_load_dwordx4 v[32:35], v[84:85], off offset:1280
	s_branch .LBB0_3114
.LBB0_3123:
	s_waitcnt vmcnt(0)
	v_add_u32_e32 v4, s13, v61
	v_ashrrev_i32_e32 v5, 31, v4
	s_ashr_i32 s6, s14, 31
	v_lshlrev_b64 v[6:7], 13, v[4:5]
	v_mov_b32_e32 v3, s6
	v_or_b32_e32 v2, s14, v66
	v_lshl_add_u64 v[6:7], s[96:97], 0, v[6:7]
	v_lshl_add_u64 v[10:11], v[2:3], 1, v[6:7]
	global_load_dwordx2 v[6:7], v[10:11], off
	v_and_b32_e32 v8, 64, v80
	v_add_u32_e32 v14, 64, v8
	v_xor_b32_e32 v1, 16, v80
	v_cmp_lt_i32_e32 vcc, v1, v14
	s_waitcnt vmcnt(0)
	v_and_b32_e32 v9, 0xffff0000, v6
	v_lshlrev_b32_e32 v8, 16, v6
	v_and_b32_e32 v13, 0xffff0000, v7
	v_lshlrev_b32_e32 v12, 16, v7
	v_pk_add_f32 v[6:7], v[58:59], v[12:13]
	v_pk_add_f32 v[8:9], v[56:57], v[8:9]
	v_cvt_pk_bf16_f32 v13, v6, v7
	v_cndmask_b32_e32 v1, v80, v1, vcc
	v_cvt_pk_bf16_f32 v12, v8, v9
	v_and_b32_e32 v9, 0xffff0000, v13
	v_and_b32_e32 v7, 0xffff0000, v12
	v_lshlrev_b32_e32 v6, 16, v12
	v_lshlrev_b32_e32 v8, 16, v13
	v_mul_f32_e32 v7, v7, v7
	v_mul_f32_e32 v9, v9, v9
	v_fmac_f32_e32 v7, v6, v6
	v_fmac_f32_e32 v9, v8, v8
	v_lshlrev_b32_e32 v1, 2, v1
	v_add_f32_e32 v6, v7, v9
	ds_bpermute_b32 v7, v1, v6
	v_xor_b32_e32 v8, 32, v80
	v_cmp_lt_i32_e32 vcc, v8, v14
	global_store_dwordx2 v[10:11], v[12:13], off
	s_waitcnt lgkmcnt(0)
	v_add_f32_e32 v7, v6, v7
	v_cndmask_b32_e32 v8, v80, v8, vcc
	v_lshlrev_b32_e32 v6, 2, v8
	ds_bpermute_b32 v8, v6, v7
	s_and_saveexec_b64 s[6:7], s[0:1]
	s_cbranch_execz .LBB0_3125
	s_waitcnt lgkmcnt(0)
	v_add_f32_e32 v7, v7, v8
	v_mul_f32_e32 v7, 0x4b800000, v7
	v_trunc_f32_e32 v7, v7
	v_mul_f32_e32 v8, 0x2f800000, v7
	v_floor_f32_e32 v9, v8
	v_fmac_f32_e32 v7, 0xcf800000, v9
	v_cvt_u32_f32_e32 v8, v7
	v_cvt_u32_f32_e32 v9, v9
	v_lshl_add_u64 v[10:11], v[4:5], 3, s[10:11]
	global_atomic_add_x2 v[10:11], v[8:9], off
